# MFMA-VALU interleave (lever 8): QK accumulator A chain issued first, first 8 exps of A placed in the B-chain MFMA gaps, all V fragment reads issued before the first PV MFMA (two V fragments in the reg
# baseline (speedup 1.0000x reference)
; #define AT_QK_LD0(kb_) do { if constexpr (NEGM) { const LAS unsigned char* kbp_ = Kl + (kb_) * KBUF + r32 * KROWB + hi * 16; AT_KLD2(0); __builtin_amdgcn_sched_barrier(0); } } while (0)
; template <int DQK, int DV, int RH, bool NEGM> ...
;     ...
;         for (int t = 0; t < NT; ++t) {
;             const int kb = t & 1;
;             if (t + 1 < NT) AT_GLOAD(t + 1);
;             f32x16 p[RH][2];
;             AT_QK_LD0(kb); AT_QK(kb); AT_VLOAD(vs_cur); AT_SOFTMAX(); AT_PV(vs_cur);
;             if (t + 1 < NT) AT_LSTORE(kb ^ 1, vs_next);
;             __syncthreads();
;             vs_prev = vs_cur; vs_cur = vs_next; vs_next = (vs_next == 2) ? 0 : vs_next + 1;
;         }
.Lmla_loop:
	ds_read_b128 v[48:51], v169 offset:13312
	ds_read_b128 v[52:55], v169 offset:13344
	ds_read_b128 v[116:119], v169 offset:13376
	ds_read_b128 v[120:123], v169 offset:13408
	s_mov_b32 m0, s70
	s_nop 0
	global_load_lds_dwordx4 v241, s[98:99]
	s_mov_b32 m0, s73
	global_load_dwordx4 v[112:115], v158, s[100:101]
	global_load_lds_dwordx4 v242, s[98:99]
	s_add_u32 s98, s98, 0x18000
	s_addc_u32 s99, s99, 0
	ds_read_b128 v[124:127], v169 offset:13440
	ds_read_b128 v[128:131], v169 offset:13472
	s_waitcnt lgkmcnt(5)
	v_mfma_f32_32x32x16_bf16 v[64:79], v[48:51], v[100:103], v[32:47]
	ds_read_b128 v[132:135], v169 offset:19968
	ds_read_b128 v[136:139], v169 offset:20000
	s_waitcnt lgkmcnt(6)
	v_mfma_f32_32x32x16_bf16 v[64:79], v[52:55], v[96:99], v[64:79]
	s_waitcnt lgkmcnt(5)
	v_mfma_f32_32x32x16_bf16 v[64:79], v[116:119], v[92:95], v[64:79]
	ds_read_b128 v[140:143], v169 offset:20032
	ds_read_b128 v[144:147], v169 offset:20064
	s_waitcnt lgkmcnt(6)
	v_mfma_f32_32x32x16_bf16 v[64:79], v[120:123], v[88:91], v[64:79]
	s_waitcnt lgkmcnt(5)
	v_mfma_f32_32x32x16_bf16 v[64:79], v[124:127], v[84:87], v[64:79]
	ds_read_b128 v[176:179], v169 offset:20096
	ds_read_b128 v[116:119], v169 offset:20128
	s_waitcnt lgkmcnt(6)
	v_mfma_f32_32x32x16_bf16 v[64:79], v[128:131], v[80:83], v[64:79]
	s_waitcnt lgkmcnt(5)
	v_mfma_f32_32x32x16_bf16 v[48:63], v[132:135], v[100:103], v[32:47]
	s_waitcnt lgkmcnt(4)
	v_mfma_f32_32x32x16_bf16 v[48:63], v[136:139], v[96:99], v[48:63]
	ds_read_b128 v[136:139], v170 offset:35840
	ds_read_b128 v[124:127], v170 offset:35872
	ds_read_b128 v[132:135], v170 offset:35904
	ds_read_b128 v[120:123], v170 offset:35936
	ds_read_b128 v[104:107], v170 offset:40512
	ds_read_b128 v[108:111], v170 offset:40544
	s_nop 1
	v_exp_f32_e32 v160, v64
	v_exp_f32_e32 v161, v65
	s_waitcnt lgkmcnt(9)
	v_mfma_f32_32x32x16_bf16 v[48:63], v[140:143], v[92:95], v[48:63]
	v_exp_f32_e32 v64, v66
	v_exp_f32_e32 v65, v67
	s_waitcnt lgkmcnt(8)
	v_mfma_f32_32x32x16_bf16 v[48:63], v[144:147], v[88:91], v[48:63]
	ds_read_b128 v[144:147], v170 offset:40448
	ds_read_b128 v[140:143], v170 offset:40480
	v_exp_f32_e32 v68, v68
	v_exp_f32_e32 v69, v69
	s_waitcnt lgkmcnt(9)
	v_mfma_f32_32x32x16_bf16 v[48:63], v[176:179], v[84:87], v[48:63]
	v_exp_f32_e32 v66, v70
	v_exp_f32_e32 v67, v71
	s_waitcnt lgkmcnt(8)
	v_mfma_f32_32x32x16_bf16 v[48:63], v[116:119], v[80:83], v[48:63]
	s_add_i32 s43, s43, 1
	v_cvt_pk_bf16_f32 v176, v160, v161
	v_cvt_pk_bf16_f32 v177, v64, v65
	v_cvt_pk_bf16_f32 v178, v68, v69
	v_cvt_pk_bf16_f32 v179, v66, v67
	v_exp_f32_e32 v70, v74
	v_exp_f32_e32 v71, v75
	s_waitcnt lgkmcnt(0)
	v_mfma_f32_32x32x16_bf16 v[16:31], v[136:139], v[176:179], v[16:31]
	v_exp_f32_e32 v136, v72
	v_exp_f32_e32 v137, v73
	v_exp_f32_e32 v74, v76
	v_exp_f32_e32 v75, v77
	v_exp_f32_e32 v72, v78
	v_exp_f32_e32 v73, v79
	v_exp_f32_e32 v76, v48
	v_mfma_f32_32x32x16_bf16 v[0:15], v[144:147], v[176:179], v[0:15]
	v_cvt_pk_bf16_f32 v144, v136, v137
	v_cvt_pk_bf16_f32 v145, v70, v71
	v_cvt_pk_bf16_f32 v146, v74, v75
	v_cvt_pk_bf16_f32 v147, v72, v73
	v_exp_f32_e32 v77, v49
	v_exp_f32_e32 v48, v50
	v_exp_f32_e32 v49, v51
	v_mfma_f32_32x32x16_bf16 v[16:31], v[124:127], v[144:147], v[16:31]
	v_exp_f32_e32 v52, v52
	v_exp_f32_e32 v53, v53
	v_exp_f32_e32 v50, v54
	v_exp_f32_e32 v51, v55
	v_cvt_pk_bf16_f32 v124, v76, v77
	v_cvt_pk_bf16_f32 v125, v48, v49
	v_cvt_pk_bf16_f32 v126, v52, v53
	v_mfma_f32_32x32x16_bf16 v[0:15], v[140:143], v[144:147], v[0:15]
	v_cvt_pk_bf16_f32 v127, v50, v51
	v_exp_f32_e32 v78, v56
	v_exp_f32_e32 v79, v57
	v_exp_f32_e32 v54, v58
	v_exp_f32_e32 v55, v59
	v_exp_f32_e32 v58, v60
	v_exp_f32_e32 v59, v61
	v_mfma_f32_32x32x16_bf16 v[16:31], v[132:135], v[124:127], v[16:31]
	v_exp_f32_e32 v56, v62
	v_exp_f32_e32 v57, v63
	v_cvt_pk_bf16_f32 v60, v78, v79
	v_cvt_pk_bf16_f32 v61, v54, v55
	v_cvt_pk_bf16_f32 v62, v58, v59
	v_cvt_pk_bf16_f32 v63, v56, v57
	v_mfma_f32_32x32x16_bf16 v[0:15], v[104:107], v[124:127], v[0:15]
	v_mfma_f32_32x32x16_bf16 v[16:31], v[120:123], v[60:63], v[16:31]
	v_mfma_f32_32x32x16_bf16 v[0:15], v[108:111], v[60:63], v[0:15]
	s_waitcnt vmcnt(0)
	ds_write2_b64 v247, v[112:113], v[114:115] offset1:2
	v_pk_add_f32 v[48:49], v[64:65], v[48:49]
	v_pk_add_f32 v[60:61], v[160:161], v[76:77]
	v_pk_add_f32 v[48:49], v[152:153], v[48:49]
	v_pk_add_f32 v[50:51], v[66:67], v[50:51]
	v_pk_add_f32 v[60:61], v[150:151], v[60:61]
	v_pk_add_f32 v[52:53], v[68:69], v[52:53]
	v_pk_add_f32 v[48:49], v[50:51], v[48:49]
	v_pk_add_f32 v[50:51], v[70:71], v[54:55]
	v_pk_add_f32 v[52:53], v[52:53], v[60:61]
	v_pk_add_f32 v[60:61], v[136:137], v[78:79]
	v_pk_add_f32 v[48:49], v[50:51], v[48:49]
	v_pk_add_f32 v[50:51], v[72:73], v[56:57]
	v_pk_add_f32 v[52:53], v[60:61], v[52:53]
	v_pk_add_f32 v[58:59], v[74:75], v[58:59]
	v_pk_add_f32 v[152:153], v[50:51], v[48:49]
	v_pk_add_f32 v[150:151], v[58:59], v[52:53]
	s_waitcnt lgkmcnt(0)
	s_barrier
; #define AT_QK_LD0(kb_) do { if constexpr (NEGM) { const LAS unsigned char* kbp_ = Kl + (kb_) * KBUF + r32 * KROWB + hi * 16; AT_KLD2(0); __builtin_amdgcn_sched_barrier(0); } } while (0)
; template <int DQK, int DV, int RH, bool NEGM> ...
;     ...
;         for (int t = 0; t < NT; ++t) {
;             const int kb = t & 1;
;             if (t + 1 < NT) AT_GLOAD(t + 1);
;             f32x16 p[RH][2];
;             AT_QK_LD0(kb); AT_QK(kb); AT_VLOAD(vs_cur); AT_SOFTMAX(); AT_PV(vs_cur);
;             if (t + 1 < NT) AT_LSTORE(kb ^ 1, vs_next);
;             __syncthreads();
;             vs_prev = vs_cur; vs_cur = vs_next; vs_next = (vs_next == 2) ? 0 : vs_next + 1;
;         }
	ds_read_b128 v[48:51], v169
	ds_read_b128 v[52:55], v169 offset:32
	ds_read_b128 v[116:119], v169 offset:64
	ds_read_b128 v[120:123], v169 offset:96
	s_add_i32 m0, s70, 13312
	s_nop 0
	global_load_lds_dwordx4 v241, s[98:99]
	s_add_i32 m0, s73, s74
	global_load_dwordx4 v[112:115], v158, s[100:101] offset:128
	global_load_lds_dwordx4 v242, s[98:99]
	s_add_u32 s98, s98, 0x18000
	s_addc_u32 s99, s99, 0
	ds_read_b128 v[124:127], v169 offset:128
	ds_read_b128 v[128:131], v169 offset:160
	s_waitcnt lgkmcnt(5)
	v_mfma_f32_32x32x16_bf16 v[64:79], v[48:51], v[100:103], v[32:47]
	ds_read_b128 v[132:135], v169 offset:6656
	ds_read_b128 v[136:139], v169 offset:6688
	s_waitcnt lgkmcnt(6)
	v_mfma_f32_32x32x16_bf16 v[64:79], v[52:55], v[96:99], v[64:79]
	s_waitcnt lgkmcnt(5)
	v_mfma_f32_32x32x16_bf16 v[64:79], v[116:119], v[92:95], v[64:79]
	ds_read_b128 v[140:143], v169 offset:6720
	ds_read_b128 v[144:147], v169 offset:6752
	s_waitcnt lgkmcnt(6)
	v_mfma_f32_32x32x16_bf16 v[64:79], v[120:123], v[88:91], v[64:79]
	s_waitcnt lgkmcnt(5)
	v_mfma_f32_32x32x16_bf16 v[64:79], v[124:127], v[84:87], v[64:79]
	ds_read_b128 v[176:179], v169 offset:6784
	ds_read_b128 v[116:119], v169 offset:6816
	s_waitcnt lgkmcnt(6)
	v_mfma_f32_32x32x16_bf16 v[64:79], v[128:131], v[80:83], v[64:79]
	s_waitcnt lgkmcnt(5)
	v_mfma_f32_32x32x16_bf16 v[48:63], v[132:135], v[100:103], v[32:47]
	s_waitcnt lgkmcnt(4)
	v_mfma_f32_32x32x16_bf16 v[48:63], v[136:139], v[96:99], v[48:63]
	ds_read_b128 v[136:139], v170 offset:45056
	ds_read_b128 v[124:127], v170 offset:45088
	ds_read_b128 v[132:135], v170 offset:45120
	ds_read_b128 v[120:123], v170 offset:45152
	ds_read_b128 v[104:107], v170 offset:49728
	ds_read_b128 v[108:111], v170 offset:49760
	s_nop 1
	v_exp_f32_e32 v160, v64
	v_exp_f32_e32 v161, v65
	s_waitcnt lgkmcnt(9)
	v_mfma_f32_32x32x16_bf16 v[48:63], v[140:143], v[92:95], v[48:63]
	v_exp_f32_e32 v64, v66
	v_exp_f32_e32 v65, v67
	s_waitcnt lgkmcnt(8)
	v_mfma_f32_32x32x16_bf16 v[48:63], v[144:147], v[88:91], v[48:63]
	ds_read_b128 v[144:147], v170 offset:49664
	ds_read_b128 v[140:143], v170 offset:49696
	v_exp_f32_e32 v68, v68
	v_exp_f32_e32 v69, v69
	s_waitcnt lgkmcnt(9)
	v_mfma_f32_32x32x16_bf16 v[48:63], v[176:179], v[84:87], v[48:63]
	v_exp_f32_e32 v66, v70
	v_exp_f32_e32 v67, v71
	s_waitcnt lgkmcnt(8)
	v_mfma_f32_32x32x16_bf16 v[48:63], v[116:119], v[80:83], v[48:63]
	s_add_i32 s43, s43, 1
	v_cvt_pk_bf16_f32 v176, v160, v161
	v_cvt_pk_bf16_f32 v177, v64, v65
	v_cvt_pk_bf16_f32 v178, v68, v69
	v_cvt_pk_bf16_f32 v179, v66, v67
	v_exp_f32_e32 v70, v74
	v_exp_f32_e32 v71, v75
	s_waitcnt lgkmcnt(0)
	v_mfma_f32_32x32x16_bf16 v[16:31], v[136:139], v[176:179], v[16:31]
	v_exp_f32_e32 v136, v72
	v_exp_f32_e32 v137, v73
	v_exp_f32_e32 v74, v76
	v_exp_f32_e32 v75, v77
	v_exp_f32_e32 v72, v78
	v_exp_f32_e32 v73, v79
	v_exp_f32_e32 v76, v48
	v_mfma_f32_32x32x16_bf16 v[0:15], v[144:147], v[176:179], v[0:15]
	v_cvt_pk_bf16_f32 v144, v136, v137
	v_cvt_pk_bf16_f32 v145, v70, v71
	v_cvt_pk_bf16_f32 v146, v74, v75
	v_cvt_pk_bf16_f32 v147, v72, v73
	v_exp_f32_e32 v77, v49
	v_exp_f32_e32 v48, v50
	v_exp_f32_e32 v49, v51
	v_mfma_f32_32x32x16_bf16 v[16:31], v[124:127], v[144:147], v[16:31]
	v_exp_f32_e32 v52, v52
	v_exp_f32_e32 v53, v53
	v_exp_f32_e32 v50, v54
	v_exp_f32_e32 v51, v55
	v_cvt_pk_bf16_f32 v124, v76, v77
	v_cvt_pk_bf16_f32 v125, v48, v49
	v_cvt_pk_bf16_f32 v126, v52, v53
	v_mfma_f32_32x32x16_bf16 v[0:15], v[140:143], v[144:147], v[0:15]
	v_cvt_pk_bf16_f32 v127, v50, v51
	v_exp_f32_e32 v78, v56
	v_exp_f32_e32 v79, v57
	v_exp_f32_e32 v54, v58
	v_exp_f32_e32 v55, v59
	v_exp_f32_e32 v58, v60
	v_exp_f32_e32 v59, v61
	v_mfma_f32_32x32x16_bf16 v[16:31], v[132:135], v[124:127], v[16:31]
	v_exp_f32_e32 v56, v62
	v_exp_f32_e32 v57, v63
	v_cvt_pk_bf16_f32 v60, v78, v79
	v_cvt_pk_bf16_f32 v61, v54, v55
	v_cvt_pk_bf16_f32 v62, v58, v59
	v_cvt_pk_bf16_f32 v63, v56, v57
	v_mfma_f32_32x32x16_bf16 v[0:15], v[104:107], v[124:127], v[0:15]
	v_mfma_f32_32x32x16_bf16 v[16:31], v[120:123], v[60:63], v[16:31]
	v_mfma_f32_32x32x16_bf16 v[0:15], v[108:111], v[60:63], v[0:15]
	s_waitcnt vmcnt(0)
	ds_write2_b64 v243, v[112:113], v[114:115] offset1:2
	v_pk_add_f32 v[48:49], v[64:65], v[48:49]
	v_pk_add_f32 v[60:61], v[160:161], v[76:77]
	v_pk_add_f32 v[48:49], v[152:153], v[48:49]
	v_pk_add_f32 v[50:51], v[66:67], v[50:51]
	v_pk_add_f32 v[60:61], v[150:151], v[60:61]
	v_pk_add_f32 v[52:53], v[68:69], v[52:53]
	v_pk_add_f32 v[48:49], v[50:51], v[48:49]
	v_pk_add_f32 v[50:51], v[70:71], v[54:55]
	v_pk_add_f32 v[52:53], v[52:53], v[60:61]
	v_pk_add_f32 v[60:61], v[136:137], v[78:79]
	v_pk_add_f32 v[48:49], v[50:51], v[48:49]
	v_pk_add_f32 v[50:51], v[72:73], v[56:57]
	v_pk_add_f32 v[52:53], v[60:61], v[52:53]
	v_pk_add_f32 v[58:59], v[74:75], v[58:59]
	v_pk_add_f32 v[152:153], v[50:51], v[48:49]
	v_pk_add_f32 v[150:151], v[58:59], v[52:53]
	s_cmp_lg_u32 s43, 63
	s_waitcnt lgkmcnt(0)
	s_barrier
	s_cbranch_scc0 .Lmla_exit
; #define AT_QK_LD0(kb_) do { if constexpr (NEGM) { const LAS unsigned char* kbp_ = Kl + (kb_) * KBUF + r32 * KROWB + hi * 16; AT_KLD2(0); __builtin_amdgcn_sched_barrier(0); } } while (0)
; template <int DQK, int DV, int RH, bool NEGM> ...
;     ...
;         for (int t = 0; t < NT; ++t) {
;             const int kb = t & 1;
;             if (t + 1 < NT) AT_GLOAD(t + 1);
;             f32x16 p[RH][2];
;             AT_QK_LD0(kb); AT_QK(kb); AT_VLOAD(vs_cur); AT_SOFTMAX(); AT_PV(vs_cur);
;             if (t + 1 < NT) AT_LSTORE(kb ^ 1, vs_next);
;             __syncthreads();
;             vs_prev = vs_cur; vs_cur = vs_next; vs_next = (vs_next == 2) ? 0 : vs_next + 1;
;         }
	ds_read_b128 v[48:51], v169 offset:13312
	ds_read_b128 v[52:55], v169 offset:13344
	ds_read_b128 v[116:119], v169 offset:13376
	ds_read_b128 v[120:123], v169 offset:13408
	s_mov_b32 m0, s70
	s_nop 0
	global_load_lds_dwordx4 v241, s[98:99]
	s_mov_b32 m0, s73
	global_load_dwordx4 v[112:115], v158, s[100:101] offset:256
	global_load_lds_dwordx4 v242, s[98:99]
	s_add_u32 s98, s98, 0x18000
	s_addc_u32 s99, s99, 0
	ds_read_b128 v[124:127], v169 offset:13440
	ds_read_b128 v[128:131], v169 offset:13472
	s_waitcnt lgkmcnt(5)
	v_mfma_f32_32x32x16_bf16 v[64:79], v[48:51], v[100:103], v[32:47]
	ds_read_b128 v[132:135], v169 offset:19968
	ds_read_b128 v[136:139], v169 offset:20000
	s_waitcnt lgkmcnt(6)
	v_mfma_f32_32x32x16_bf16 v[64:79], v[52:55], v[96:99], v[64:79]
	s_waitcnt lgkmcnt(5)
	v_mfma_f32_32x32x16_bf16 v[64:79], v[116:119], v[92:95], v[64:79]
	ds_read_b128 v[140:143], v169 offset:20032
	ds_read_b128 v[144:147], v169 offset:20064
	s_waitcnt lgkmcnt(6)
	v_mfma_f32_32x32x16_bf16 v[64:79], v[120:123], v[88:91], v[64:79]
	s_waitcnt lgkmcnt(5)
	v_mfma_f32_32x32x16_bf16 v[64:79], v[124:127], v[84:87], v[64:79]
	ds_read_b128 v[176:179], v169 offset:20096
	ds_read_b128 v[116:119], v169 offset:20128
	s_waitcnt lgkmcnt(6)
	v_mfma_f32_32x32x16_bf16 v[64:79], v[128:131], v[80:83], v[64:79]
	s_waitcnt lgkmcnt(5)
	v_mfma_f32_32x32x16_bf16 v[48:63], v[132:135], v[100:103], v[32:47]
	s_waitcnt lgkmcnt(4)
	v_mfma_f32_32x32x16_bf16 v[48:63], v[136:139], v[96:99], v[48:63]
	ds_read_b128 v[136:139], v170 offset:26624
	ds_read_b128 v[124:127], v170 offset:26656
	ds_read_b128 v[132:135], v170 offset:26688
	ds_read_b128 v[120:123], v170 offset:26720
	ds_read_b128 v[104:107], v170 offset:31296
	ds_read_b128 v[108:111], v170 offset:31328
	s_nop 1
	v_exp_f32_e32 v160, v64
	v_exp_f32_e32 v161, v65
	s_waitcnt lgkmcnt(9)
	v_mfma_f32_32x32x16_bf16 v[48:63], v[140:143], v[92:95], v[48:63]
	v_exp_f32_e32 v64, v66
	v_exp_f32_e32 v65, v67
	s_waitcnt lgkmcnt(8)
	v_mfma_f32_32x32x16_bf16 v[48:63], v[144:147], v[88:91], v[48:63]
	ds_read_b128 v[144:147], v170 offset:31232
	ds_read_b128 v[140:143], v170 offset:31264
	v_exp_f32_e32 v68, v68
	v_exp_f32_e32 v69, v69
	s_waitcnt lgkmcnt(9)
	v_mfma_f32_32x32x16_bf16 v[48:63], v[176:179], v[84:87], v[48:63]
	v_exp_f32_e32 v66, v70
	v_exp_f32_e32 v67, v71
	s_waitcnt lgkmcnt(8)
	v_mfma_f32_32x32x16_bf16 v[48:63], v[116:119], v[80:83], v[48:63]
	s_add_i32 s43, s43, 1
	v_cvt_pk_bf16_f32 v176, v160, v161
	v_cvt_pk_bf16_f32 v177, v64, v65
	v_cvt_pk_bf16_f32 v178, v68, v69
	v_cvt_pk_bf16_f32 v179, v66, v67
	v_exp_f32_e32 v70, v74
	v_exp_f32_e32 v71, v75
	s_waitcnt lgkmcnt(0)
	v_mfma_f32_32x32x16_bf16 v[16:31], v[136:139], v[176:179], v[16:31]
	v_exp_f32_e32 v136, v72
	v_exp_f32_e32 v137, v73
	v_exp_f32_e32 v74, v76
	v_exp_f32_e32 v75, v77
	v_exp_f32_e32 v72, v78
	v_exp_f32_e32 v73, v79
	v_exp_f32_e32 v76, v48
	v_mfma_f32_32x32x16_bf16 v[0:15], v[144:147], v[176:179], v[0:15]
	v_cvt_pk_bf16_f32 v144, v136, v137
	v_cvt_pk_bf16_f32 v145, v70, v71
	v_cvt_pk_bf16_f32 v146, v74, v75
	v_cvt_pk_bf16_f32 v147, v72, v73
	v_exp_f32_e32 v77, v49
	v_exp_f32_e32 v48, v50
	v_exp_f32_e32 v49, v51
	v_mfma_f32_32x32x16_bf16 v[16:31], v[124:127], v[144:147], v[16:31]
	v_exp_f32_e32 v52, v52
	v_exp_f32_e32 v53, v53
	v_exp_f32_e32 v50, v54
	v_exp_f32_e32 v51, v55
	v_cvt_pk_bf16_f32 v124, v76, v77
	v_cvt_pk_bf16_f32 v125, v48, v49
	v_cvt_pk_bf16_f32 v126, v52, v53
	v_mfma_f32_32x32x16_bf16 v[0:15], v[140:143], v[144:147], v[0:15]
	v_cvt_pk_bf16_f32 v127, v50, v51
	v_exp_f32_e32 v78, v56
	v_exp_f32_e32 v79, v57
	v_exp_f32_e32 v54, v58
	v_exp_f32_e32 v55, v59
	v_exp_f32_e32 v58, v60
	v_exp_f32_e32 v59, v61
	v_mfma_f32_32x32x16_bf16 v[16:31], v[132:135], v[124:127], v[16:31]
	v_exp_f32_e32 v56, v62
	v_exp_f32_e32 v57, v63
	v_cvt_pk_bf16_f32 v60, v78, v79
	v_cvt_pk_bf16_f32 v61, v54, v55
	v_cvt_pk_bf16_f32 v62, v58, v59
	v_cvt_pk_bf16_f32 v63, v56, v57
	v_mfma_f32_32x32x16_bf16 v[0:15], v[104:107], v[124:127], v[0:15]
	v_mfma_f32_32x32x16_bf16 v[16:31], v[120:123], v[60:63], v[16:31]
	v_mfma_f32_32x32x16_bf16 v[0:15], v[108:111], v[60:63], v[0:15]
	s_waitcnt vmcnt(0)
	ds_write2_b64 v246, v[112:113], v[114:115] offset1:2
	v_pk_add_f32 v[48:49], v[64:65], v[48:49]
	v_pk_add_f32 v[60:61], v[160:161], v[76:77]
	v_pk_add_f32 v[48:49], v[152:153], v[48:49]
	v_pk_add_f32 v[50:51], v[66:67], v[50:51]
	v_pk_add_f32 v[60:61], v[150:151], v[60:61]
	v_pk_add_f32 v[52:53], v[68:69], v[52:53]
	v_pk_add_f32 v[48:49], v[50:51], v[48:49]
	v_pk_add_f32 v[50:51], v[70:71], v[54:55]
	v_pk_add_f32 v[52:53], v[52:53], v[60:61]
	v_pk_add_f32 v[60:61], v[136:137], v[78:79]
	v_pk_add_f32 v[48:49], v[50:51], v[48:49]
	v_pk_add_f32 v[50:51], v[72:73], v[56:57]
	v_pk_add_f32 v[52:53], v[60:61], v[52:53]
	v_pk_add_f32 v[58:59], v[74:75], v[58:59]
	v_pk_add_f32 v[152:153], v[50:51], v[48:49]
	v_pk_add_f32 v[150:151], v[58:59], v[52:53]
	s_waitcnt lgkmcnt(0)
	s_barrier
; #define AT_QK_LD0(kb_) do { if constexpr (NEGM) { const LAS unsigned char* kbp_ = Kl + (kb_) * KBUF + r32 * KROWB + hi * 16; AT_KLD2(0); __builtin_amdgcn_sched_barrier(0); } } while (0)
; template <int DQK, int DV, int RH, bool NEGM> ...
;     ...
;         for (int t = 0; t < NT; ++t) {
;             const int kb = t & 1;
;             if (t + 1 < NT) AT_GLOAD(t + 1);
;             f32x16 p[RH][2];
;             AT_QK_LD0(kb); AT_QK(kb); AT_VLOAD(vs_cur); AT_SOFTMAX(); AT_PV(vs_cur);
;             if (t + 1 < NT) AT_LSTORE(kb ^ 1, vs_next);
;             __syncthreads();
;             vs_prev = vs_cur; vs_cur = vs_next; vs_next = (vs_next == 2) ? 0 : vs_next + 1;
;         }
	ds_read_b128 v[48:51], v169
	ds_read_b128 v[52:55], v169 offset:32
	ds_read_b128 v[116:119], v169 offset:64
	ds_read_b128 v[120:123], v169 offset:96
	s_add_i32 m0, s70, 13312
	s_nop 0
	global_load_lds_dwordx4 v241, s[98:99]
	s_add_i32 m0, s73, s74
	global_load_dwordx4 v[112:115], v158, s[100:101] offset:384
	global_load_lds_dwordx4 v242, s[98:99]
	s_add_u32 s98, s98, 0x18000
	s_addc_u32 s99, s99, 0
	ds_read_b128 v[124:127], v169 offset:128
	ds_read_b128 v[128:131], v169 offset:160
	s_waitcnt lgkmcnt(5)
	v_mfma_f32_32x32x16_bf16 v[64:79], v[48:51], v[100:103], v[32:47]
	ds_read_b128 v[132:135], v169 offset:6656
	ds_read_b128 v[136:139], v169 offset:6688
	s_waitcnt lgkmcnt(6)
	v_mfma_f32_32x32x16_bf16 v[64:79], v[52:55], v[96:99], v[64:79]
	s_waitcnt lgkmcnt(5)
	v_mfma_f32_32x32x16_bf16 v[64:79], v[116:119], v[92:95], v[64:79]
	ds_read_b128 v[140:143], v169 offset:6720
	ds_read_b128 v[144:147], v169 offset:6752
	s_waitcnt lgkmcnt(6)
	v_mfma_f32_32x32x16_bf16 v[64:79], v[120:123], v[88:91], v[64:79]
	s_waitcnt lgkmcnt(5)
	v_mfma_f32_32x32x16_bf16 v[64:79], v[124:127], v[84:87], v[64:79]
	ds_read_b128 v[176:179], v169 offset:6784
	ds_read_b128 v[116:119], v169 offset:6816
	s_waitcnt lgkmcnt(6)
	v_mfma_f32_32x32x16_bf16 v[64:79], v[128:131], v[80:83], v[64:79]
	s_waitcnt lgkmcnt(5)
	v_mfma_f32_32x32x16_bf16 v[48:63], v[132:135], v[100:103], v[32:47]
	s_waitcnt lgkmcnt(4)
	v_mfma_f32_32x32x16_bf16 v[48:63], v[136:139], v[96:99], v[48:63]
	ds_read_b128 v[136:139], v170 offset:35840
	ds_read_b128 v[124:127], v170 offset:35872
	ds_read_b128 v[132:135], v170 offset:35904
	ds_read_b128 v[120:123], v170 offset:35936
	ds_read_b128 v[104:107], v170 offset:40512
	ds_read_b128 v[108:111], v170 offset:40544
	s_nop 1
	v_exp_f32_e32 v160, v64
	v_exp_f32_e32 v161, v65
	s_waitcnt lgkmcnt(9)
	v_mfma_f32_32x32x16_bf16 v[48:63], v[140:143], v[92:95], v[48:63]
	v_exp_f32_e32 v64, v66
	v_exp_f32_e32 v65, v67
	s_waitcnt lgkmcnt(8)
	v_mfma_f32_32x32x16_bf16 v[48:63], v[144:147], v[88:91], v[48:63]
	ds_read_b128 v[144:147], v170 offset:40448
	ds_read_b128 v[140:143], v170 offset:40480
	v_exp_f32_e32 v68, v68
	v_exp_f32_e32 v69, v69
	s_waitcnt lgkmcnt(9)
	v_mfma_f32_32x32x16_bf16 v[48:63], v[176:179], v[84:87], v[48:63]
	v_exp_f32_e32 v66, v70
	v_exp_f32_e32 v67, v71
	s_waitcnt lgkmcnt(8)
	v_mfma_f32_32x32x16_bf16 v[48:63], v[116:119], v[80:83], v[48:63]
	s_add_i32 s43, s43, 1
	v_cvt_pk_bf16_f32 v176, v160, v161
	v_cvt_pk_bf16_f32 v177, v64, v65
	v_cvt_pk_bf16_f32 v178, v68, v69
	v_cvt_pk_bf16_f32 v179, v66, v67
	v_exp_f32_e32 v70, v74
	v_exp_f32_e32 v71, v75
	s_waitcnt lgkmcnt(0)
	v_mfma_f32_32x32x16_bf16 v[16:31], v[136:139], v[176:179], v[16:31]
	v_exp_f32_e32 v136, v72
	v_exp_f32_e32 v137, v73
	v_exp_f32_e32 v74, v76
	v_exp_f32_e32 v75, v77
	v_exp_f32_e32 v72, v78
	v_exp_f32_e32 v73, v79
	v_exp_f32_e32 v76, v48
	v_mfma_f32_32x32x16_bf16 v[0:15], v[144:147], v[176:179], v[0:15]
	v_cvt_pk_bf16_f32 v144, v136, v137
	v_cvt_pk_bf16_f32 v145, v70, v71
	v_cvt_pk_bf16_f32 v146, v74, v75
	v_cvt_pk_bf16_f32 v147, v72, v73
	v_exp_f32_e32 v77, v49
	v_exp_f32_e32 v48, v50
	v_exp_f32_e32 v49, v51
	v_mfma_f32_32x32x16_bf16 v[16:31], v[124:127], v[144:147], v[16:31]
	v_exp_f32_e32 v52, v52
	v_exp_f32_e32 v53, v53
	v_exp_f32_e32 v50, v54
	v_exp_f32_e32 v51, v55
	v_cvt_pk_bf16_f32 v124, v76, v77
	v_cvt_pk_bf16_f32 v125, v48, v49
	v_cvt_pk_bf16_f32 v126, v52, v53
	v_mfma_f32_32x32x16_bf16 v[0:15], v[140:143], v[144:147], v[0:15]
	v_cvt_pk_bf16_f32 v127, v50, v51
	v_exp_f32_e32 v78, v56
	v_exp_f32_e32 v79, v57
	v_exp_f32_e32 v54, v58
	v_exp_f32_e32 v55, v59
	v_exp_f32_e32 v58, v60
	v_exp_f32_e32 v59, v61
	v_mfma_f32_32x32x16_bf16 v[16:31], v[132:135], v[124:127], v[16:31]
	v_exp_f32_e32 v56, v62
	v_exp_f32_e32 v57, v63
	v_cvt_pk_bf16_f32 v60, v78, v79
	v_cvt_pk_bf16_f32 v61, v54, v55
	v_cvt_pk_bf16_f32 v62, v58, v59
	v_cvt_pk_bf16_f32 v63, v56, v57
	v_mfma_f32_32x32x16_bf16 v[0:15], v[104:107], v[124:127], v[0:15]
	v_mfma_f32_32x32x16_bf16 v[16:31], v[120:123], v[60:63], v[16:31]
	v_mfma_f32_32x32x16_bf16 v[0:15], v[108:111], v[60:63], v[0:15]
	s_waitcnt vmcnt(0)
	ds_write2_b64 v247, v[112:113], v[114:115] offset1:2
	v_pk_add_f32 v[48:49], v[64:65], v[48:49]
	v_pk_add_f32 v[60:61], v[160:161], v[76:77]
	v_pk_add_f32 v[48:49], v[152:153], v[48:49]
	v_pk_add_f32 v[50:51], v[66:67], v[50:51]
	v_pk_add_f32 v[60:61], v[150:151], v[60:61]
	v_pk_add_f32 v[52:53], v[68:69], v[52:53]
	v_pk_add_f32 v[48:49], v[50:51], v[48:49]
	v_pk_add_f32 v[50:51], v[70:71], v[54:55]
	v_pk_add_f32 v[52:53], v[52:53], v[60:61]
	v_pk_add_f32 v[60:61], v[136:137], v[78:79]
	v_pk_add_f32 v[48:49], v[50:51], v[48:49]
	v_pk_add_f32 v[50:51], v[72:73], v[56:57]
	v_pk_add_f32 v[52:53], v[60:61], v[52:53]
	v_pk_add_f32 v[58:59], v[74:75], v[58:59]
	v_pk_add_f32 v[152:153], v[50:51], v[48:49]
	v_pk_add_f32 v[150:151], v[58:59], v[52:53]
	s_waitcnt lgkmcnt(0)
	s_barrier
; #define AT_QK_LD0(kb_) do { if constexpr (NEGM) { const LAS unsigned char* kbp_ = Kl + (kb_) * KBUF + r32 * KROWB + hi * 16; AT_KLD2(0); __builtin_amdgcn_sched_barrier(0); } } while (0)
; template <int DQK, int DV, int RH, bool NEGM> ...
;     ...
;         for (int t = 0; t < NT; ++t) {
;             const int kb = t & 1;
;             if (t + 1 < NT) AT_GLOAD(t + 1);
;             f32x16 p[RH][2];
;             AT_QK_LD0(kb); AT_QK(kb); AT_VLOAD(vs_cur); AT_SOFTMAX(); AT_PV(vs_cur);
;             if (t + 1 < NT) AT_LSTORE(kb ^ 1, vs_next);
;             __syncthreads();
;             vs_prev = vs_cur; vs_cur = vs_next; vs_next = (vs_next == 2) ? 0 : vs_next + 1;
;         }
	ds_read_b128 v[48:51], v169 offset:13312
	ds_read_b128 v[52:55], v169 offset:13344
	ds_read_b128 v[116:119], v169 offset:13376
	ds_read_b128 v[120:123], v169 offset:13408
	s_mov_b32 m0, s70
	s_nop 0
	global_load_lds_dwordx4 v241, s[98:99]
	s_mov_b32 m0, s73
	global_load_dwordx4 v[112:115], v158, s[100:101] offset:512
	global_load_lds_dwordx4 v242, s[98:99]
	s_add_u32 s98, s98, 0x18000
	s_addc_u32 s99, s99, 0
	ds_read_b128 v[124:127], v169 offset:13440
	ds_read_b128 v[128:131], v169 offset:13472
	s_waitcnt lgkmcnt(5)
	v_mfma_f32_32x32x16_bf16 v[64:79], v[48:51], v[100:103], v[32:47]
	ds_read_b128 v[132:135], v169 offset:19968
	ds_read_b128 v[136:139], v169 offset:20000
	s_waitcnt lgkmcnt(6)
	v_mfma_f32_32x32x16_bf16 v[64:79], v[52:55], v[96:99], v[64:79]
	s_waitcnt lgkmcnt(5)
	v_mfma_f32_32x32x16_bf16 v[64:79], v[116:119], v[92:95], v[64:79]
	ds_read_b128 v[140:143], v169 offset:20032
	ds_read_b128 v[144:147], v169 offset:20064
	s_waitcnt lgkmcnt(6)
	v_mfma_f32_32x32x16_bf16 v[64:79], v[120:123], v[88:91], v[64:79]
	s_waitcnt lgkmcnt(5)
	v_mfma_f32_32x32x16_bf16 v[64:79], v[124:127], v[84:87], v[64:79]
	ds_read_b128 v[176:179], v169 offset:20096
	ds_read_b128 v[116:119], v169 offset:20128
	s_waitcnt lgkmcnt(6)
	v_mfma_f32_32x32x16_bf16 v[64:79], v[128:131], v[80:83], v[64:79]
	s_waitcnt lgkmcnt(5)
	v_mfma_f32_32x32x16_bf16 v[48:63], v[132:135], v[100:103], v[32:47]
	s_waitcnt lgkmcnt(4)
	v_mfma_f32_32x32x16_bf16 v[48:63], v[136:139], v[96:99], v[48:63]
	ds_read_b128 v[136:139], v170 offset:45056
	ds_read_b128 v[124:127], v170 offset:45088
	ds_read_b128 v[132:135], v170 offset:45120
	ds_read_b128 v[120:123], v170 offset:45152
	ds_read_b128 v[104:107], v170 offset:49728
	ds_read_b128 v[108:111], v170 offset:49760
	s_nop 1
	v_exp_f32_e32 v160, v64
	v_exp_f32_e32 v161, v65
	s_waitcnt lgkmcnt(9)
	v_mfma_f32_32x32x16_bf16 v[48:63], v[140:143], v[92:95], v[48:63]
	v_exp_f32_e32 v64, v66
	v_exp_f32_e32 v65, v67
	s_waitcnt lgkmcnt(8)
	v_mfma_f32_32x32x16_bf16 v[48:63], v[144:147], v[88:91], v[48:63]
	ds_read_b128 v[144:147], v170 offset:49664
	ds_read_b128 v[140:143], v170 offset:49696
	v_exp_f32_e32 v68, v68
	v_exp_f32_e32 v69, v69
	s_waitcnt lgkmcnt(9)
	v_mfma_f32_32x32x16_bf16 v[48:63], v[176:179], v[84:87], v[48:63]
	v_exp_f32_e32 v66, v70
	v_exp_f32_e32 v67, v71
	s_waitcnt lgkmcnt(8)
	v_mfma_f32_32x32x16_bf16 v[48:63], v[116:119], v[80:83], v[48:63]
	s_add_i32 s43, s43, 1
	v_cvt_pk_bf16_f32 v176, v160, v161
	v_cvt_pk_bf16_f32 v177, v64, v65
	v_cvt_pk_bf16_f32 v178, v68, v69
	v_cvt_pk_bf16_f32 v179, v66, v67
	v_exp_f32_e32 v70, v74
	v_exp_f32_e32 v71, v75
	s_waitcnt lgkmcnt(0)
	v_mfma_f32_32x32x16_bf16 v[16:31], v[136:139], v[176:179], v[16:31]
	v_exp_f32_e32 v136, v72
	v_exp_f32_e32 v137, v73
	v_exp_f32_e32 v74, v76
	v_exp_f32_e32 v75, v77
	v_exp_f32_e32 v72, v78
	v_exp_f32_e32 v73, v79
	v_exp_f32_e32 v76, v48
	v_mfma_f32_32x32x16_bf16 v[0:15], v[144:147], v[176:179], v[0:15]
	v_cvt_pk_bf16_f32 v144, v136, v137
	v_cvt_pk_bf16_f32 v145, v70, v71
	v_cvt_pk_bf16_f32 v146, v74, v75
	v_cvt_pk_bf16_f32 v147, v72, v73
	v_exp_f32_e32 v77, v49
	v_exp_f32_e32 v48, v50
	v_exp_f32_e32 v49, v51
	v_mfma_f32_32x32x16_bf16 v[16:31], v[124:127], v[144:147], v[16:31]
	v_exp_f32_e32 v52, v52
	v_exp_f32_e32 v53, v53
	v_exp_f32_e32 v50, v54
	v_exp_f32_e32 v51, v55
	v_cvt_pk_bf16_f32 v124, v76, v77
	v_cvt_pk_bf16_f32 v125, v48, v49
	v_cvt_pk_bf16_f32 v126, v52, v53
	v_mfma_f32_32x32x16_bf16 v[0:15], v[140:143], v[144:147], v[0:15]
	v_cvt_pk_bf16_f32 v127, v50, v51
	v_exp_f32_e32 v78, v56
	v_exp_f32_e32 v79, v57
	v_exp_f32_e32 v54, v58
	v_exp_f32_e32 v55, v59
	v_exp_f32_e32 v58, v60
	v_exp_f32_e32 v59, v61
	v_mfma_f32_32x32x16_bf16 v[16:31], v[132:135], v[124:127], v[16:31]
	v_exp_f32_e32 v56, v62
	v_exp_f32_e32 v57, v63
	v_cvt_pk_bf16_f32 v60, v78, v79
	v_cvt_pk_bf16_f32 v61, v54, v55
	v_cvt_pk_bf16_f32 v62, v58, v59
	v_cvt_pk_bf16_f32 v63, v56, v57
	v_mfma_f32_32x32x16_bf16 v[0:15], v[104:107], v[124:127], v[0:15]
	v_mfma_f32_32x32x16_bf16 v[16:31], v[120:123], v[60:63], v[16:31]
	v_mfma_f32_32x32x16_bf16 v[0:15], v[108:111], v[60:63], v[0:15]
	s_waitcnt vmcnt(0)
	ds_write2_b64 v243, v[112:113], v[114:115] offset1:2
	v_pk_add_f32 v[48:49], v[64:65], v[48:49]
	v_pk_add_f32 v[60:61], v[160:161], v[76:77]
	v_pk_add_f32 v[48:49], v[152:153], v[48:49]
	v_pk_add_f32 v[50:51], v[66:67], v[50:51]
	v_pk_add_f32 v[60:61], v[150:151], v[60:61]
	v_pk_add_f32 v[52:53], v[68:69], v[52:53]
	v_pk_add_f32 v[48:49], v[50:51], v[48:49]
	v_pk_add_f32 v[50:51], v[70:71], v[54:55]
	v_pk_add_f32 v[52:53], v[52:53], v[60:61]
	v_pk_add_f32 v[60:61], v[136:137], v[78:79]
	v_pk_add_f32 v[48:49], v[50:51], v[48:49]
	v_pk_add_f32 v[50:51], v[72:73], v[56:57]
	v_pk_add_f32 v[52:53], v[60:61], v[52:53]
	v_pk_add_f32 v[58:59], v[74:75], v[58:59]
	v_pk_add_f32 v[152:153], v[50:51], v[48:49]
	v_pk_add_f32 v[150:151], v[58:59], v[52:53]
	s_waitcnt lgkmcnt(0)
	s_barrier
	ds_read_b128 v[48:51], v169
	ds_read_b128 v[52:55], v169 offset:32
	ds_read_b128 v[116:119], v169 offset:64
	ds_read_b128 v[120:123], v169 offset:96
	s_add_i32 m0, s70, 13312
	s_nop 0
	global_load_lds_dwordx4 v241, s[98:99]
	s_add_i32 m0, s73, s74
	global_load_dwordx4 v[112:115], v158, s[100:101] offset:640
	global_load_lds_dwordx4 v242, s[98:99]
	s_add_u32 s98, s98, 0x18000
	s_addc_u32 s99, s99, 0
	ds_read_b128 v[124:127], v169 offset:128
	ds_read_b128 v[128:131], v169 offset:160
	s_waitcnt lgkmcnt(5)
	v_mfma_f32_32x32x16_bf16 v[64:79], v[48:51], v[100:103], v[32:47]
	ds_read_b128 v[132:135], v169 offset:6656
	ds_read_b128 v[136:139], v169 offset:6688
	s_waitcnt lgkmcnt(6)
	v_mfma_f32_32x32x16_bf16 v[64:79], v[52:55], v[96:99], v[64:79]
	s_waitcnt lgkmcnt(5)
	v_mfma_f32_32x32x16_bf16 v[64:79], v[116:119], v[92:95], v[64:79]
	ds_read_b128 v[140:143], v169 offset:6720
	ds_read_b128 v[144:147], v169 offset:6752
	s_waitcnt lgkmcnt(6)
	v_mfma_f32_32x32x16_bf16 v[64:79], v[120:123], v[88:91], v[64:79]
	s_waitcnt lgkmcnt(5)
	v_mfma_f32_32x32x16_bf16 v[64:79], v[124:127], v[84:87], v[64:79]
	ds_read_b128 v[176:179], v169 offset:6784
	ds_read_b128 v[116:119], v169 offset:6816
	s_waitcnt lgkmcnt(6)
	v_mfma_f32_32x32x16_bf16 v[64:79], v[128:131], v[80:83], v[64:79]
	s_waitcnt lgkmcnt(5)
	v_mfma_f32_32x32x16_bf16 v[48:63], v[132:135], v[100:103], v[32:47]
	s_waitcnt lgkmcnt(4)
	v_mfma_f32_32x32x16_bf16 v[48:63], v[136:139], v[96:99], v[48:63]
	ds_read_b128 v[136:139], v170 offset:26624
	ds_read_b128 v[124:127], v170 offset:26656
	ds_read_b128 v[132:135], v170 offset:26688
	ds_read_b128 v[120:123], v170 offset:26720
	ds_read_b128 v[104:107], v170 offset:31296
	ds_read_b128 v[108:111], v170 offset:31328
	s_nop 1
	v_exp_f32_e32 v160, v64
	v_exp_f32_e32 v161, v65
	s_waitcnt lgkmcnt(9)
	v_mfma_f32_32x32x16_bf16 v[48:63], v[140:143], v[92:95], v[48:63]
	v_exp_f32_e32 v64, v66
	v_exp_f32_e32 v65, v67
	s_waitcnt lgkmcnt(8)
	v_mfma_f32_32x32x16_bf16 v[48:63], v[144:147], v[88:91], v[48:63]
	ds_read_b128 v[144:147], v170 offset:31232
	ds_read_b128 v[140:143], v170 offset:31264
	v_exp_f32_e32 v68, v68
	v_exp_f32_e32 v69, v69
	s_waitcnt lgkmcnt(9)
	v_mfma_f32_32x32x16_bf16 v[48:63], v[176:179], v[84:87], v[48:63]
	v_exp_f32_e32 v66, v70
	v_exp_f32_e32 v67, v71
	s_waitcnt lgkmcnt(8)
	v_mfma_f32_32x32x16_bf16 v[48:63], v[116:119], v[80:83], v[48:63]
	s_add_i32 s43, s43, 1
	v_cvt_pk_bf16_f32 v176, v160, v161
	v_cvt_pk_bf16_f32 v177, v64, v65
	v_cvt_pk_bf16_f32 v178, v68, v69
	v_cvt_pk_bf16_f32 v179, v66, v67
	v_exp_f32_e32 v70, v74
	v_exp_f32_e32 v71, v75
	s_waitcnt lgkmcnt(0)
	v_mfma_f32_32x32x16_bf16 v[16:31], v[136:139], v[176:179], v[16:31]
	v_exp_f32_e32 v136, v72
	v_exp_f32_e32 v137, v73
	v_exp_f32_e32 v74, v76
	v_exp_f32_e32 v75, v77
	v_exp_f32_e32 v72, v78
	v_exp_f32_e32 v73, v79
	v_exp_f32_e32 v76, v48
	v_mfma_f32_32x32x16_bf16 v[0:15], v[144:147], v[176:179], v[0:15]
	v_cvt_pk_bf16_f32 v144, v136, v137
	v_cvt_pk_bf16_f32 v145, v70, v71
	v_cvt_pk_bf16_f32 v146, v74, v75
	v_cvt_pk_bf16_f32 v147, v72, v73
	v_exp_f32_e32 v77, v49
	v_exp_f32_e32 v48, v50
	v_exp_f32_e32 v49, v51
	v_mfma_f32_32x32x16_bf16 v[16:31], v[124:127], v[144:147], v[16:31]
	v_exp_f32_e32 v52, v52
	v_exp_f32_e32 v53, v53
	v_exp_f32_e32 v50, v54
	v_exp_f32_e32 v51, v55
	v_cvt_pk_bf16_f32 v124, v76, v77
	v_cvt_pk_bf16_f32 v125, v48, v49
	v_cvt_pk_bf16_f32 v126, v52, v53
	v_mfma_f32_32x32x16_bf16 v[0:15], v[140:143], v[144:147], v[0:15]
	v_cvt_pk_bf16_f32 v127, v50, v51
	v_exp_f32_e32 v78, v56
	v_exp_f32_e32 v79, v57
	v_exp_f32_e32 v54, v58
	v_exp_f32_e32 v55, v59
	v_exp_f32_e32 v58, v60
	v_exp_f32_e32 v59, v61
	v_mfma_f32_32x32x16_bf16 v[16:31], v[132:135], v[124:127], v[16:31]
	v_exp_f32_e32 v56, v62
	v_exp_f32_e32 v57, v63
	v_cvt_pk_bf16_f32 v60, v78, v79
	v_cvt_pk_bf16_f32 v61, v54, v55
	v_cvt_pk_bf16_f32 v62, v58, v59
	v_cvt_pk_bf16_f32 v63, v56, v57
	v_mfma_f32_32x32x16_bf16 v[0:15], v[104:107], v[124:127], v[0:15]
	v_mfma_f32_32x32x16_bf16 v[16:31], v[120:123], v[60:63], v[16:31]
	v_mfma_f32_32x32x16_bf16 v[0:15], v[108:111], v[60:63], v[0:15]
	s_waitcnt vmcnt(0)
	ds_write2_b64 v246, v[112:113], v[114:115] offset1:2
	v_pk_add_f32 v[48:49], v[64:65], v[48:49]
	v_pk_add_f32 v[60:61], v[160:161], v[76:77]
	v_pk_add_f32 v[48:49], v[152:153], v[48:49]
	v_pk_add_f32 v[50:51], v[66:67], v[50:51]
	v_pk_add_f32 v[60:61], v[150:151], v[60:61]
	v_pk_add_f32 v[52:53], v[68:69], v[52:53]
	v_pk_add_f32 v[48:49], v[50:51], v[48:49]
	v_pk_add_f32 v[50:51], v[70:71], v[54:55]
	v_pk_add_f32 v[52:53], v[52:53], v[60:61]
	v_pk_add_f32 v[60:61], v[136:137], v[78:79]
	v_pk_add_f32 v[48:49], v[50:51], v[48:49]
	v_pk_add_f32 v[50:51], v[72:73], v[56:57]
	v_pk_add_f32 v[52:53], v[60:61], v[52:53]
	v_pk_add_f32 v[58:59], v[74:75], v[58:59]
	v_pk_add_f32 v[152:153], v[50:51], v[48:49]
	v_pk_add_f32 v[150:151], v[58:59], v[52:53]
	v_max3_f32 v148, v150, v151, v152
	v_max_f32_e32 v148, v148, v153
	v_cmp_nge_f32_e32 vcc, 0x49800000, v148
	s_cbranch_vccnz .Lmla_renorm
